# attention tile loop: waves 4-7 start half a tile later (s_sleep 6) so the two waves of a SIMD alternate MFMA and softmax VALU
# speedup vs baseline: 1.0076x; 1.0021x over previous
.LBB0_874:
	v_readfirstlane_b32 s6, v158
	s_nop 3
	s_cmp_ge_u32 s6, 0x100
	s_cbranch_scc0 .Lmy_stg_skip
	s_sleep 6
